# speedup vs baseline: 1.0034x; 1.0027x over previous
.LBB0_183:
	s_or_b64 exec, exec, s[6:7]
	s_bfe_u32 s3, s2, 0x20004
	s_and_b32 s18, s2, 15
	v_mov_b32_e32 v143, v131
	s_not_b32 s2, s2
	s_lshl_b32 s2, s2, 2
	v_ashrrev_i32_e32 v32, 6, v143
	s_lshl_b32 s6, s3, 13
	s_and_b32 s2, s2, 0x1f00
	v_lshlrev_b32_e32 v0, 5, v32
	s_or_b32 s34, s6, s2
	v_ashrrev_i32_e32 v1, 31, v0
	v_lshl_add_u64 v[132:133], s[34:35], 0, v[0:1]
	v_lshlrev_b64 v[2:3], 11, v[132:133]
	v_and_b32_e32 v148, 31, v143
	v_lshl_add_u64 v[2:3], s[12:13], 0, v[2:3]
	s_lshl_b32 s34, s18, 7
	v_bfe_u32 v146, v143, 5, 1
	v_lshl_add_u64 v[2:3], v[2:3], 0, s[34:35]
	v_lshlrev_b32_e32 v128, 11, v148
	v_lshl_add_u64 v[2:3], v[2:3], 0, v[128:129]
	v_lshlrev_b32_e32 v128, 4, v146
	v_lshl_add_u64 v[14:15], v[2:3], 0, v[128:129]
	global_load_dwordx4 v[2:5], v[14:15], off nt
	global_load_dwordx4 v[6:9], v[14:15], off offset:32 nt
	global_load_dwordx4 v[10:13], v[14:15], off offset:64 nt
	s_nop 0
	global_load_dwordx4 v[14:17], v[14:15], off offset:96 nt
	v_and_b32_e32 v1, 32, v143
	global_load_dwordx4 v[18:21], v1, s[68:69] offset:16
	global_load_dwordx4 v[22:25], v1, s[68:69]
	global_load_dwordx4 v[206:209], v1, s[68:69] offset:64
	global_load_dwordx4 v[210:213], v1, s[68:69] offset:80
	global_load_dwordx4 v[214:217], v1, s[68:69] offset:128
	global_load_dwordx4 v[218:221], v1, s[68:69] offset:144
	global_load_dwordx4 v[222:225], v1, s[68:69] offset:192
	global_load_dwordx4 v[226:229], v1, s[68:69] offset:208
	s_lshl_b32 s6, s3, 19
	s_add_u32 s6, s76, s6
	s_addc_u32 s7, s71, 0
	s_lshl_b32 s8, s18, 15
	s_add_u32 s38, s6, s8
	s_addc_u32 s39, s7, 0
	s_lshl_b32 s6, s2, 2
	v_and_b32_e32 v144, 63, v143
	v_mov_b32_e32 v245, s6
	global_load_dword v246, v245, s[38:39]
	v_lshlrev_b32_e32 v245, 8, v144
	global_load_dword v247, v245, s[38:39] offset:252
	v_or_b32_e32 v245, 64, v144
	v_lshlrev_b32_e32 v245, 8, v245
	global_load_dword v244, v245, s[38:39] offset:252
	s_mov_b64 s[8:9], 0
	s_waitcnt vmcnt(14)
	v_and_b32_e32 v27, 0xffff0000, v2
	v_lshlrev_b32_e32 v26, 16, v2
	s_waitcnt vmcnt(13)
	v_lshlrev_b32_e32 v39, 16, v8
	v_and_b32_e32 v40, 0xffff0000, v8
	v_mul_f32_e32 v8, v27, v27
	v_lshlrev_b32_e32 v28, 16, v3
	v_fmac_f32_e32 v8, v26, v26
	v_and_b32_e32 v29, 0xffff0000, v3
	v_fmac_f32_e32 v8, v28, v28
	v_lshlrev_b32_e32 v30, 16, v4
	v_fmac_f32_e32 v8, v29, v29
	v_and_b32_e32 v31, 0xffff0000, v4
	v_fmac_f32_e32 v8, v30, v30
	v_lshlrev_b32_e32 v33, 16, v5
	v_fmac_f32_e32 v8, v31, v31
	v_and_b32_e32 v34, 0xffff0000, v5
	v_fmac_f32_e32 v8, v33, v33
	v_lshlrev_b32_e32 v35, 16, v6
	v_fmac_f32_e32 v8, v34, v34
	v_and_b32_e32 v36, 0xffff0000, v6
	v_fmac_f32_e32 v8, v35, v35
	v_lshlrev_b32_e32 v37, 16, v7
	v_fmac_f32_e32 v8, v36, v36
	v_and_b32_e32 v38, 0xffff0000, v7
	v_fmac_f32_e32 v8, v37, v37
	v_fmac_f32_e32 v8, v38, v38
	v_fmac_f32_e32 v8, v39, v39
	v_lshlrev_b32_e32 v41, 16, v9
	v_fmac_f32_e32 v8, v40, v40
	v_and_b32_e32 v42, 0xffff0000, v9
	v_fmac_f32_e32 v8, v41, v41
	s_waitcnt vmcnt(12)
	v_lshlrev_b32_e32 v43, 16, v10
	v_fmac_f32_e32 v8, v42, v42
	v_and_b32_e32 v44, 0xffff0000, v10
	v_fmac_f32_e32 v8, v43, v43
	v_lshlrev_b32_e32 v45, 16, v11
	v_fmac_f32_e32 v8, v44, v44
	v_and_b32_e32 v46, 0xffff0000, v11
	v_fmac_f32_e32 v8, v45, v45
	v_lshlrev_b32_e32 v47, 16, v12
	v_fmac_f32_e32 v8, v46, v46
	v_and_b32_e32 v48, 0xffff0000, v12
	v_fmac_f32_e32 v8, v47, v47
	v_lshlrev_b32_e32 v49, 16, v13
	v_fmac_f32_e32 v8, v48, v48
	v_and_b32_e32 v50, 0xffff0000, v13
	v_fmac_f32_e32 v8, v49, v49
	s_waitcnt vmcnt(11)
	v_lshlrev_b32_e32 v51, 16, v14
	v_fmac_f32_e32 v8, v50, v50
	v_and_b32_e32 v52, 0xffff0000, v14
	v_and_b32_e32 v10, 0xffff0000, v15
	v_lshlrev_b32_e32 v11, 16, v15
	v_fmac_f32_e32 v8, v51, v51
	v_pk_mul_f32 v[2:3], v[10:11], v[10:11]
	v_fmac_f32_e32 v8, v52, v52
	v_and_b32_e32 v12, 0xffff0000, v16
	v_lshlrev_b32_e32 v13, 16, v16
	v_add_f32_e32 v3, v3, v8
	v_pk_mul_f32 v[4:5], v[12:13], v[12:13]
	v_add_f32_e32 v2, v2, v3
	v_and_b32_e32 v14, 0xffff0000, v17
	v_lshlrev_b32_e32 v15, 16, v17
	v_add_f32_e32 v2, v5, v2
	v_pk_mul_f32 v[6:7], v[14:15], v[14:15]
	v_add_f32_e32 v2, v4, v2
	v_add_f32_e32 v2, v7, v2
	v_add_f32_e32 v2, v6, v2
	v_mov_b32_e32 v3, v2
	s_nop 1
	v_permlane32_swap_b32_e32 v2, v3
	v_add_f32_e32 v2, v2, v3
	v_fmamk_f32 v2, v2, 0x3c800000, v130
	v_mul_f32_e32 v3, 0x4b800000, v2
	v_cmp_gt_f32_e32 vcc, s89, v2
	s_nop 1
	v_cndmask_b32_e32 v2, v2, v3, vcc
	v_rsq_f32_e32 v2, v2
	s_nop 0
	v_mul_f32_e32 v3, 0x45800000, v2
	v_cndmask_b32_e32 v16, v2, v3, vcc
	v_mul_f32_e32 v2, v16, v26
	v_mul_f32_e32 v3, v16, v27
	v_mul_f32_e32 v4, v16, v28
	v_mul_f32_e32 v5, v16, v29
	v_mul_f32_e32 v6, v16, v30
	v_mul_f32_e32 v7, v16, v31
	v_mul_f32_e32 v8, v16, v33
	v_mul_f32_e32 v9, v16, v34
	s_waitcnt vmcnt(9)
	v_mul_f32_e32 v2, v22, v2
	v_mul_f32_e32 v3, v23, v3
	v_mul_f32_e32 v4, v24, v4
	v_mul_f32_e32 v5, v25, v5
	v_mul_f32_e32 v6, v18, v6
	v_mul_f32_e32 v7, v19, v7
	v_mul_f32_e32 v8, v20, v8
	v_mul_f32_e32 v9, v21, v9
	v_cvt_pk_bf16_f32 v96, v2, v3
	v_cvt_pk_bf16_f32 v97, v4, v5
	v_cvt_pk_bf16_f32 v98, v6, v7
	v_cvt_pk_bf16_f32 v99, v8, v9
	s_waitcnt vmcnt(7)
	v_mov_b32_e32 v2, v206
	v_mov_b32_e32 v3, v207
	v_mov_b32_e32 v4, v208
	v_mov_b32_e32 v5, v209
	v_mov_b32_e32 v6, v210
	v_mov_b32_e32 v7, v211
	v_mov_b32_e32 v8, v212
	v_mov_b32_e32 v9, v213
	v_mul_f32_e32 v17, v16, v35
	v_mul_f32_e32 v18, v16, v36
	v_mul_f32_e32 v19, v16, v37
	v_mul_f32_e32 v20, v16, v38
	v_mul_f32_e32 v21, v16, v39
	v_mul_f32_e32 v22, v16, v40
	v_mul_f32_e32 v23, v16, v41
	v_mul_f32_e32 v24, v16, v42
	v_mul_f32_e32 v11, v16, v11
	v_mul_f32_e32 v10, v16, v10
	v_mul_f32_e32 v13, v16, v13
	v_mul_f32_e32 v12, v16, v12
	v_mul_f32_e32 v15, v16, v15
	v_mul_f32_e32 v14, v16, v14
	v_mul_f32_e32 v2, v2, v17
	v_mul_f32_e32 v3, v3, v18
	v_mul_f32_e32 v4, v4, v19
	v_mul_f32_e32 v5, v5, v20
	v_mul_f32_e32 v6, v6, v21
	v_mul_f32_e32 v7, v7, v22
	v_mul_f32_e32 v8, v8, v23
	v_mul_f32_e32 v9, v9, v24
	v_cvt_pk_bf16_f32 v100, v2, v3
	v_cvt_pk_bf16_f32 v101, v4, v5
	v_cvt_pk_bf16_f32 v102, v6, v7
	v_cvt_pk_bf16_f32 v103, v8, v9
	s_waitcnt vmcnt(5)
	v_mov_b32_e32 v2, v214
	v_mov_b32_e32 v3, v215
	v_mov_b32_e32 v4, v216
	v_mov_b32_e32 v5, v217
	v_mov_b32_e32 v6, v218
	v_mov_b32_e32 v7, v219
	v_mov_b32_e32 v8, v220
	v_mov_b32_e32 v9, v221
	v_mul_f32_e32 v17, v16, v43
	v_mul_f32_e32 v18, v16, v44
	v_mul_f32_e32 v19, v16, v45
	v_mul_f32_e32 v20, v16, v46
	v_mul_f32_e32 v21, v16, v47
	v_mul_f32_e32 v22, v16, v48
	v_mul_f32_e32 v23, v16, v49
	v_mul_f32_e32 v24, v16, v50
	v_mul_f32_e32 v2, v17, v2
	v_mul_f32_e32 v3, v18, v3
	v_mul_f32_e32 v4, v19, v4
	v_mul_f32_e32 v5, v20, v5
	v_mul_f32_e32 v6, v21, v6
	v_mul_f32_e32 v7, v22, v7
	v_mul_f32_e32 v8, v23, v8
	v_mul_f32_e32 v9, v24, v9
	v_cvt_pk_bf16_f32 v104, v2, v3
	v_cvt_pk_bf16_f32 v105, v4, v5
	v_cvt_pk_bf16_f32 v106, v6, v7
	v_cvt_pk_bf16_f32 v107, v8, v9
	s_waitcnt vmcnt(3)
	v_mov_b32_e32 v2, v222
	v_mov_b32_e32 v3, v223
	v_mov_b32_e32 v4, v224
	v_mov_b32_e32 v5, v225
	v_mov_b32_e32 v6, v226
	v_mov_b32_e32 v7, v227
	v_mov_b32_e32 v8, v228
	v_mov_b32_e32 v9, v229
	v_mov_b32_e32 v1, s6
	v_mul_f32_e32 v17, v16, v51
	v_mul_f32_e32 v18, v16, v52
	s_add_i32 s6, s2, 0x100
	s_lshr_b32 s77, s6, 6
	v_cmp_gt_u32_e32 vcc, s77, v144
	s_mov_b64 s[6:7], 0
	v_mul_f32_e32 v2, v17, v2
	v_mul_f32_e32 v3, v18, v3
	v_mul_f32_e32 v4, v11, v4
	v_mul_f32_e32 v5, v10, v5
	v_mul_f32_e32 v6, v13, v6
	v_mul_f32_e32 v7, v12, v7
	v_mul_f32_e32 v8, v15, v8
	v_mul_f32_e32 v9, v14, v9
	v_cvt_pk_bf16_f32 v108, v2, v3
	v_cvt_pk_bf16_f32 v109, v4, v5
	v_cvt_pk_bf16_f32 v110, v6, v7
	v_cvt_pk_bf16_f32 v111, v8, v9
	s_waitcnt vmcnt(0)
	v_mov_b32_e32 v1, v246
	s_and_saveexec_b64 s[10:11], vcc
	s_cbranch_execz .LBB0_185
	v_mov_b32_e32 v2, v247
	v_sub_f32_e32 v2, v2, v1
	v_mul_f32_e32 v2, 0x3e000000, v2
	v_cmp_lt_f32_e64 s[8:9], v2, -v142
	s_and_b64 s[8:9], s[8:9], exec
